# GEMM main loops: odd k-tile LDS fragment reads issued ahead of the even->odd workgroup barrier (slot already complete)
# speedup vs baseline: 1.0036x; 1.0036x over previous
.LBB0_162:
	s_mul_i32 s2, s40, 0x6000
	v_or_b32_e32 v192, s2, v195
	v_add_u32_e32 v193, v192, v196
	ds_read_b128 v[188:191], v193 offset:16384
	ds_read_b128 v[200:203], v193 offset:18432
	v_add_u32_e32 v193, s2, v194
	v_add_u32_e32 v216, v193, v196
	ds_read_b128 v[204:207], v216
	ds_read_b128 v[208:211], v216 offset:2048
	ds_read_b128 v[212:215], v216 offset:4096
	ds_read_b128 v[240:243], v216 offset:6144
	s_add_i32 s2, s40, 1
	s_waitcnt lgkmcnt(3)
	v_mfma_f32_32x32x16_bf16 v[64:79], v[188:191], v[204:207], v[64:79]
	v_add_u32_e32 v192, v192, v197
	v_mfma_f32_32x32x16_bf16 v[112:127], v[200:203], v[204:207], v[112:127]
	ds_read_b128 v[204:207], v192 offset:16384
	ds_read_b128 v[244:247], v192 offset:18432
	s_waitcnt lgkmcnt(4)
	v_mfma_f32_32x32x16_bf16 v[96:111], v[188:191], v[208:211], v[96:111]
	v_add_u32_e32 v192, v193, v197
	v_mfma_f32_32x32x16_bf16 v[80:95], v[200:203], v[208:211], v[80:95]
	ds_read_b128 v[208:211], v192
	ds_read_b128 v[248:251], v192 offset:2048
	s_waitcnt lgkmcnt(5)
	v_mfma_f32_32x32x16_bf16 v[48:63], v[188:191], v[212:215], v[48:63]
	v_mfma_f32_32x32x16_bf16 v[32:47], v[200:203], v[212:215], v[32:47]
	ds_read_b128 v[212:215], v192 offset:4096
	ds_read_b128 v[234:237], v192 offset:6144
	s_waitcnt lgkmcnt(6)
	v_mfma_f32_32x32x16_bf16 v[16:31], v[188:191], v[240:243], v[16:31]
	v_mfma_f32_32x32x16_bf16 v[0:15], v[200:203], v[240:243], v[0:15]
	s_waitcnt lgkmcnt(3)
	v_mfma_f32_32x32x16_bf16 v[64:79], v[204:207], v[208:211], v[64:79]
	v_mfma_f32_32x32x16_bf16 v[112:127], v[244:247], v[208:211], v[112:127]
	s_waitcnt lgkmcnt(2)
	v_mfma_f32_32x32x16_bf16 v[96:111], v[204:207], v[248:251], v[96:111]
	v_mfma_f32_32x32x16_bf16 v[80:95], v[244:247], v[248:251], v[80:95]
	s_waitcnt lgkmcnt(1)
	v_mfma_f32_32x32x16_bf16 v[48:63], v[204:207], v[212:215], v[48:63]
	v_mfma_f32_32x32x16_bf16 v[32:47], v[244:247], v[212:215], v[32:47]
	s_cmp_lt_i32 s40, 2
	s_cselect_b32 s2, s2, 0
	s_add_i32 s40, s2, 1
	s_add_i32 s3, s2, -2
	s_cmp_gt_i32 s2, 0
	s_cselect_b32 s44, -1, 2
	s_min_u32 s45, s29, 13
	s_add_i32 s44, s44, s2
	s_lshl_b32 s84, s45, 7
	s_cmp_gt_i32 s2, 1
	s_mul_i32 s41, s2, 0x6000
	s_cselect_b32 s2, s3, s40
	v_mov_b32_e32 v188, s2
	v_mov_b32_e32 v189, s44
	v_cndmask_b32_e64 v188, v188, v189, s[42:43]
	v_mad_u64_u32 v[192:193], s[2:3], v188, s9, v[182:183]
	v_or_b32_e32 v193, s41, v195
	v_add_u32_e32 v216, s41, v194
	s_waitcnt lgkmcnt(0)
	v_mfma_f32_32x32x16_bf16 v[16:31], v[204:207], v[234:237], v[16:31]
	v_add_u32_e32 v200, v193, v196
	v_add_u32_e32 v217, v216, v196
	ds_read_b128 v[188:191], v200 offset:16384
	ds_read_b128 v[200:203], v200 offset:18432
	ds_read_b128 v[204:207], v217
	ds_read_b128 v[208:211], v217 offset:2048
	ds_read_b128 v[212:215], v217 offset:4096
	s_barrier
	v_mfma_f32_32x32x16_bf16 v[0:15], v[244:247], v[234:237], v[0:15]
	ds_read_b128 v[234:237], v217 offset:6144
	s_waitcnt lgkmcnt(3)
	v_mfma_f32_32x32x16_bf16 v[64:79], v[188:191], v[204:207], v[64:79]
	v_add_u32_e32 v193, v193, v197
	v_mfma_f32_32x32x16_bf16 v[112:127], v[200:203], v[204:207], v[112:127]
	ds_read_b128 v[204:207], v193 offset:16384
	ds_read_b128 v[240:243], v193 offset:18432
	s_waitcnt lgkmcnt(4)
	v_mfma_f32_32x32x16_bf16 v[96:111], v[188:191], v[208:211], v[96:111]
	v_add_u32_e32 v193, v216, v197
	v_mfma_f32_32x32x16_bf16 v[80:95], v[200:203], v[208:211], v[80:95]
	ds_read_b128 v[208:211], v193
	ds_read_b128 v[244:247], v193 offset:2048
	s_waitcnt lgkmcnt(5)
	v_mfma_f32_32x32x16_bf16 v[48:63], v[188:191], v[212:215], v[48:63]
	v_mfma_f32_32x32x16_bf16 v[32:47], v[200:203], v[212:215], v[32:47]
	ds_read_b128 v[212:215], v193 offset:4096
	ds_read_b128 v[248:251], v193 offset:6144
	s_waitcnt lgkmcnt(6)
	v_mfma_f32_32x32x16_bf16 v[16:31], v[188:191], v[234:237], v[16:31]
	s_waitcnt vmcnt(11)
	ds_write_b128 v192, v[142:145]
	s_waitcnt vmcnt(10)
	ds_write_b128 v192, v[130:133] offset:2048
	s_waitcnt vmcnt(9)
	ds_write_b128 v192, v[134:137] offset:4096
	v_mfma_f32_32x32x16_bf16 v[0:15], v[200:203], v[234:237], v[0:15]
	s_waitcnt lgkmcnt(6)
	v_mfma_f32_32x32x16_bf16 v[64:79], v[204:207], v[208:211], v[64:79]
	s_waitcnt vmcnt(8)
	ds_write_b128 v192, v[138:141] offset:6144
	s_waitcnt vmcnt(7)
	ds_write_b128 v192, v[146:149] offset:8192
	s_waitcnt vmcnt(6)
	ds_write_b128 v192, v[150:153] offset:10240
	v_mfma_f32_32x32x16_bf16 v[112:127], v[240:243], v[208:211], v[112:127]
	s_waitcnt lgkmcnt(8)
	v_mfma_f32_32x32x16_bf16 v[96:111], v[204:207], v[244:247], v[96:111]
	s_waitcnt vmcnt(5)
	ds_write_b128 v192, v[154:157] offset:12288
	s_waitcnt vmcnt(4)
	ds_write_b128 v192, v[162:165] offset:14336
	s_waitcnt vmcnt(3)
	ds_write_b128 v192, v[158:161] offset:16384
	v_mfma_f32_32x32x16_bf16 v[80:95], v[240:243], v[244:247], v[80:95]
	s_waitcnt lgkmcnt(10)
	v_mfma_f32_32x32x16_bf16 v[48:63], v[204:207], v[212:215], v[48:63]
	s_waitcnt vmcnt(2)
	ds_write_b128 v192, v[166:169] offset:18432
	s_waitcnt vmcnt(1)
	ds_write_b128 v192, v[170:173] offset:20480
	s_waitcnt vmcnt(0)
	ds_write_b128 v192, v[174:177] offset:22528
	v_mfma_f32_32x32x16_bf16 v[32:47], v[240:243], v[212:215], v[32:47]
	v_lshl_add_u64 v[158:159], v[178:179], 0, s[84:85]
	v_add_co_u32_e32 v130, vcc, s96, v158
	global_load_dwordx4 v[142:145], v[158:159], off offset:256
	s_nop 0
	v_addc_co_u32_e32 v131, vcc, 0, v159, vcc
	v_add_co_u32_e32 v134, vcc, s97, v158
	v_lshl_add_u64 v[174:175], v[180:181], 0, s[84:85]
	s_nop 0
	v_addc_co_u32_e32 v135, vcc, 0, v159, vcc
	v_add_co_u32_e32 v138, vcc, s4, v158
	global_load_dwordx4 v[130:133], v[130:131], off offset:256
	s_nop 0
	v_addc_co_u32_e32 v139, vcc, 0, v159, vcc
	v_add_co_u32_e32 v146, vcc, s5, v158
	global_load_dwordx4 v[134:137], v[134:135], off offset:256
	s_nop 0
	v_addc_co_u32_e32 v147, vcc, 0, v159, vcc
	v_add_co_u32_e32 v150, vcc, s6, v158
	global_load_dwordx4 v[138:141], v[138:139], off offset:256
	s_nop 0
	v_addc_co_u32_e32 v151, vcc, 0, v159, vcc
	v_add_co_u32_e32 v154, vcc, s7, v158
	global_load_dwordx4 v[146:149], v[146:147], off offset:256
	s_nop 0
	v_addc_co_u32_e32 v155, vcc, 0, v159, vcc
	v_add_co_u32_e32 v158, vcc, s8, v158
	global_load_dwordx4 v[150:153], v[150:151], off offset:256
	s_nop 0
	v_addc_co_u32_e32 v159, vcc, 0, v159, vcc
	v_add_co_u32_e32 v166, vcc, s96, v174
	global_load_dwordx4 v[154:157], v[154:155], off offset:256
	s_nop 0
	v_addc_co_u32_e32 v167, vcc, 0, v175, vcc
	v_add_co_u32_e32 v170, vcc, s97, v174
	global_load_dwordx4 v[162:165], v[158:159], off offset:256
	s_nop 0
	global_load_dwordx4 v[158:161], v[174:175], off offset:256
	v_addc_co_u32_e32 v171, vcc, 0, v175, vcc
	v_add_co_u32_e32 v174, vcc, s4, v174
	global_load_dwordx4 v[166:169], v[166:167], off offset:256
	s_nop 0
	v_addc_co_u32_e32 v175, vcc, 0, v175, vcc
	global_load_dwordx4 v[170:173], v[170:171], off offset:256
	s_waitcnt lgkmcnt(12)
	v_mfma_f32_32x32x16_bf16 v[16:31], v[204:207], v[248:251], v[16:31]
	global_load_dwordx4 v[174:177], v[174:175], off offset:256
	s_waitcnt lgkmcnt(0)
	s_cselect_b32 s40, 0, s40
	s_add_i32 s29, s29, 1
	s_cmp_eq_u32 s29, 16
	s_barrier
	v_mfma_f32_32x32x16_bf16 v[0:15], v[240:243], v[248:251], v[0:15]
	s_cbranch_scc0 .LBB0_162
	s_setprio 0
	v_readlane_b32 s2, v254, 2
	s_add_i32 s25, s25, s2
	s_cmpk_gt_i32 s25, 0xc7f
	s_cselect_b64 s[40:41], -1, 0
	s_cmpk_lt_i32 s25, 0xc80
	s_mov_b32 s29, s26
	s_mov_b32 s55, s27
	s_mov_b32 s54, s28
	v_readlane_b32 s3, v254, 3
	s_cbranch_scc0 .LBB0_165
	s_ashr_i32 s2, s25, 3
	s_mul_hi_i32 s3, s2, 0x51eb851f
	s_lshr_b32 s29, s3, 31
	s_ashr_i32 s3, s3, 6
	s_add_i32 s45, s3, s29
	s_mul_i32 s3, s45, 0xc8
	s_sub_i32 s2, s2, s3
	s_ashr_i32 s3, s2, 6
	s_lshl_b32 s29, s3, 3
	s_and_b32 s44, s25, 7
	s_sub_i32 s46, 25, s29
	s_cmp_gt_i32 s3, 2
	s_cselect_b32 s46, s46, 8
	s_waitcnt vmcnt(10)
	v_cvt_f32_ubyte0_e32 v130, s46
	v_rcp_iflag_f32_e32 v131, v130
	s_and_b32 s47, s2, 63
	v_cvt_f32_ubyte0_e32 v132, s47
	v_mul_f32_e32 v131, v132, v131
	v_trunc_f32_e32 v131, v131
	v_cvt_u32_f32_e32 v133, v131
	v_fma_f32 v131, -v131, v130, v132
	v_cmp_ge_f32_e64 s[2:3], |v131|, v130
	s_cmp_lg_u64 s[2:3], 0
	v_readfirstlane_b32 s48, v133
	s_addc_u32 s2, s48, 0
	s_and_b32 s3, s2, 0xff
	s_mul_i32 s2, s2, s46
	s_sub_i32 s2, s47, s2
	s_and_b32 s2, s2, 0xff
	s_add_i32 s29, s29, s2
	s_lshl_b32 s2, s45, 6
	s_lshl_b32 s3, s3, 3
	s_add_i32 s3, s3, s2
	s_or_b32 s2, s3, s44
	s_lshl_b32 s54, s2, 8
	v_add_u32_e32 v130, s54, v183
	v_ashrrev_i32_e32 v131, 31, v130
	s_lshl_b32 s55, s29, 7
	v_lshlrev_b64 v[130:131], 11, v[130:131]
	v_lshl_add_u64 v[178:179], v[184:185], 0, v[130:131]
	v_add_u32_e32 v130, s55, v183
	v_ashrrev_i32_e32 v131, 31, v130
	v_lshlrev_b64 v[130:131], 11, v[130:131]
	v_lshl_add_u64 v[180:181], v[186:187], 0, v[130:131]
	v_add_co_u32_e32 v130, vcc, s96, v178
	s_nop 1
	v_addc_co_u32_e32 v131, vcc, 0, v179, vcc
	s_waitcnt vmcnt(9)
	v_add_co_u32_e32 v134, vcc, s97, v178
	s_nop 1
	v_addc_co_u32_e32 v135, vcc, 0, v179, vcc
	s_waitcnt vmcnt(8)
	v_add_co_u32_e32 v138, vcc, s4, v178
	global_load_dwordx4 v[130:133], v[130:131], off
	s_nop 0
	global_load_dwordx4 v[134:137], v[134:135], off
	v_addc_co_u32_e32 v139, vcc, 0, v179, vcc
	v_add_co_u32_e32 v142, vcc, s5, v178
	s_nop 1
	v_addc_co_u32_e32 v143, vcc, 0, v179, vcc
	global_load_dwordx4 v[138:141], v[138:139], off
	s_nop 0
	global_load_dwordx4 v[146:149], v[142:143], off
	v_add_co_u32_e32 v142, vcc, 0x50000, v178
	s_nop 1
	v_addc_co_u32_e32 v143, vcc, 0, v179, vcc
	v_add_co_u32_e32 v144, vcc, 0x60000, v178
	s_nop 1
	v_addc_co_u32_e32 v145, vcc, 0, v179, vcc
	s_waitcnt vmcnt(8)
	v_add_co_u32_e32 v162, vcc, 0x70000, v178
	global_load_dwordx4 v[150:153], v[142:143], off
	global_load_dwordx4 v[154:157], v[144:145], off
	v_addc_co_u32_e32 v163, vcc, 0, v179, vcc
	s_waitcnt vmcnt(8)
	v_add_co_u32_e32 v166, vcc, 0x10000, v180
	global_load_dwordx4 v[142:145], v[178:179], off
	global_load_dwordx4 v[158:161], v[180:181], off
	v_addc_co_u32_e32 v167, vcc, 0, v181, vcc
	s_waitcnt vmcnt(9)
	v_add_co_u32_e32 v170, vcc, 0x20000, v180
	global_load_dwordx4 v[162:165], v[162:163], off
	s_nop 0
	global_load_dwordx4 v[166:169], v[166:167], off
	v_addc_co_u32_e32 v171, vcc, 0, v181, vcc
	s_waitcnt vmcnt(10)
	v_add_co_u32_e32 v174, vcc, 0x30000, v180
	s_nop 1
	v_addc_co_u32_e32 v175, vcc, 0, v181, vcc
	global_load_dwordx4 v[170:173], v[170:171], off
	s_nop 0
	global_load_dwordx4 v[174:177], v[174:175], off

.LBB0_975:
	s_mul_i32 s2, s29, 0x6000
	v_or_b32_e32 v234, s2, v193
	v_add_u32_e32 v240, s2, v192
	v_add_u32_e32 v198, v234, v194
	v_add_u32_e32 v214, v240, v194
	ds_read_b128 v[188:191], v198 offset:16384
	ds_read_b128 v[198:201], v198 offset:18432
	ds_read_b128 v[202:205], v214
	ds_read_b128 v[206:209], v214 offset:2048
	ds_read_b128 v[210:213], v214 offset:4096
	ds_read_b128 v[214:217], v214 offset:6144
	s_add_i32 s2, s29, 1
	s_waitcnt lgkmcnt(0)
	v_mfma_f32_32x32x16_bf16 v[112:127], v[188:191], v[202:205], v[112:127]
	v_add_u32_e32 v234, v234, v195
	v_mfma_f32_32x32x16_bf16 v[96:111], v[198:201], v[202:205], v[96:111]
	ds_read_b128 v[202:205], v234 offset:16384
	ds_read_b128 v[234:237], v234 offset:18432
	v_mfma_f32_32x32x16_bf16 v[80:95], v[188:191], v[206:209], v[80:95]
	v_add_u32_e32 v244, v240, v195
	v_mfma_f32_32x32x16_bf16 v[64:79], v[198:201], v[206:209], v[64:79]
	ds_read_b128 v[206:209], v244
	ds_read_b128 v[240:243], v244 offset:2048
	v_mfma_f32_32x32x16_bf16 v[48:63], v[188:191], v[210:213], v[48:63]
	v_mfma_f32_32x32x16_bf16 v[32:47], v[198:201], v[210:213], v[32:47]
	ds_read_b128 v[210:213], v244 offset:4096
	ds_read_b128 v[244:247], v244 offset:6144
	v_mfma_f32_32x32x16_bf16 v[16:31], v[188:191], v[214:217], v[16:31]
	v_mfma_f32_32x32x16_bf16 v[0:15], v[198:201], v[214:217], v[0:15]
	s_waitcnt lgkmcnt(3)
	v_mfma_f32_32x32x16_bf16 v[112:127], v[202:205], v[206:209], v[112:127]
	v_mfma_f32_32x32x16_bf16 v[96:111], v[234:237], v[206:209], v[96:111]
	s_waitcnt lgkmcnt(2)
	v_mfma_f32_32x32x16_bf16 v[80:95], v[202:205], v[240:243], v[80:95]
	v_mfma_f32_32x32x16_bf16 v[64:79], v[234:237], v[240:243], v[64:79]
	s_waitcnt lgkmcnt(1)
	v_mfma_f32_32x32x16_bf16 v[48:63], v[202:205], v[210:213], v[48:63]
	v_mfma_f32_32x32x16_bf16 v[32:47], v[234:237], v[210:213], v[32:47]
	s_cmp_lt_i32 s29, 2
	s_cselect_b32 s2, s2, 0
	s_add_i32 s29, s2, 1
	s_add_i32 s3, s2, -2
	s_cmp_gt_i32 s2, 0
	s_cselect_b32 s39, -1, 2
	s_min_u32 s40, s28, 13
	s_add_i32 s39, s39, s2
	s_lshl_b32 s84, s40, 7
	s_cmp_gt_i32 s2, 1
	s_mul_i32 s38, s2, 0x6000
	s_cselect_b32 s2, s3, s29
	s_waitcnt lgkmcnt(0)
	v_mfma_f32_32x32x16_bf16 v[0:15], v[234:237], v[244:247], v[0:15]
	v_mov_b32_e32 v188, s2
	v_mov_b32_e32 v189, s39
	v_or_b32_e32 v234, s38, v193
	v_add_u32_e32 v240, s38, v192
	v_cndmask_b32_e64 v188, v188, v189, s[42:43]
	v_add_u32_e32 v198, v234, v194
	v_add_u32_e32 v214, v240, v194
	v_mfma_f32_32x32x16_bf16 v[16:31], v[202:205], v[244:247], v[16:31]
	v_mad_u64_u32 v[248:249], s[2:3], v188, s9, v[182:183]
	ds_read_b128 v[188:191], v198 offset:16384
	ds_read_b128 v[198:201], v198 offset:18432
	ds_read_b128 v[202:205], v214
	ds_read_b128 v[206:209], v214 offset:2048
	ds_read_b128 v[210:213], v214 offset:4096
	ds_read_b128 v[214:217], v214 offset:6144
	s_barrier
	s_waitcnt lgkmcnt(3)
	v_mfma_f32_32x32x16_bf16 v[112:127], v[188:191], v[202:205], v[112:127]
	v_add_u32_e32 v234, v234, v195
	v_mfma_f32_32x32x16_bf16 v[96:111], v[198:201], v[202:205], v[96:111]
	ds_read_b128 v[202:205], v234 offset:16384
	ds_read_b128 v[234:237], v234 offset:18432
	s_waitcnt lgkmcnt(4)
	v_mfma_f32_32x32x16_bf16 v[80:95], v[188:191], v[206:209], v[80:95]
	v_add_u32_e32 v244, v240, v195
	v_mfma_f32_32x32x16_bf16 v[64:79], v[198:201], v[206:209], v[64:79]
	ds_read_b128 v[206:209], v244
	ds_read_b128 v[240:243], v244 offset:2048
	s_waitcnt lgkmcnt(5)
	v_mfma_f32_32x32x16_bf16 v[48:63], v[188:191], v[210:213], v[48:63]
	v_mfma_f32_32x32x16_bf16 v[32:47], v[198:201], v[210:213], v[32:47]
	ds_read_b128 v[210:213], v244 offset:4096
	ds_read_b128 v[244:247], v244 offset:6144
	s_waitcnt lgkmcnt(6)
	v_mfma_f32_32x32x16_bf16 v[16:31], v[188:191], v[214:217], v[16:31]
	s_waitcnt vmcnt(11)
	ds_write_b128 v248, v[142:145]
	s_waitcnt vmcnt(10)
	ds_write_b128 v248, v[130:133] offset:2048
	s_waitcnt vmcnt(9)
	ds_write_b128 v248, v[134:137] offset:4096
	v_mfma_f32_32x32x16_bf16 v[0:15], v[198:201], v[214:217], v[0:15]
	s_waitcnt lgkmcnt(6)
	v_mfma_f32_32x32x16_bf16 v[112:127], v[202:205], v[206:209], v[112:127]
	s_waitcnt vmcnt(8)
	ds_write_b128 v248, v[138:141] offset:6144
	s_waitcnt vmcnt(7)
	ds_write_b128 v248, v[146:149] offset:8192
	s_waitcnt vmcnt(6)
	ds_write_b128 v248, v[150:153] offset:10240
	v_mfma_f32_32x32x16_bf16 v[96:111], v[234:237], v[206:209], v[96:111]
	s_waitcnt lgkmcnt(8)
	v_mfma_f32_32x32x16_bf16 v[80:95], v[202:205], v[240:243], v[80:95]
	s_waitcnt vmcnt(5)
	ds_write_b128 v248, v[154:157] offset:12288
	s_waitcnt vmcnt(4)
	ds_write_b128 v248, v[162:165] offset:14336
	s_waitcnt vmcnt(3)
	ds_write_b128 v248, v[158:161] offset:16384
	v_mfma_f32_32x32x16_bf16 v[64:79], v[234:237], v[240:243], v[64:79]
	s_waitcnt lgkmcnt(10)
	v_mfma_f32_32x32x16_bf16 v[48:63], v[202:205], v[210:213], v[48:63]
	s_waitcnt vmcnt(2)
	ds_write_b128 v248, v[166:169] offset:18432
	s_waitcnt vmcnt(1)
	ds_write_b128 v248, v[170:173] offset:20480
	s_waitcnt vmcnt(0)
	ds_write_b128 v248, v[174:177] offset:22528
	v_mfma_f32_32x32x16_bf16 v[32:47], v[234:237], v[210:213], v[32:47]
	v_lshl_add_u64 v[158:159], v[178:179], 0, s[84:85]
	v_add_co_u32_e32 v130, vcc, s96, v158
	global_load_dwordx4 v[142:145], v[158:159], off offset:256
	s_nop 0
	v_addc_co_u32_e32 v131, vcc, 0, v159, vcc
	v_add_co_u32_e32 v134, vcc, s97, v158
	v_lshl_add_u64 v[174:175], v[180:181], 0, s[84:85]
	s_nop 0
	v_addc_co_u32_e32 v135, vcc, 0, v159, vcc
	v_add_co_u32_e32 v138, vcc, s4, v158
	global_load_dwordx4 v[130:133], v[130:131], off offset:256
	s_nop 0
	v_addc_co_u32_e32 v139, vcc, 0, v159, vcc
	v_add_co_u32_e32 v146, vcc, s5, v158
	global_load_dwordx4 v[134:137], v[134:135], off offset:256
	s_nop 0
	v_addc_co_u32_e32 v147, vcc, 0, v159, vcc
	v_add_co_u32_e32 v150, vcc, s6, v158
	global_load_dwordx4 v[138:141], v[138:139], off offset:256
	s_nop 0
	v_addc_co_u32_e32 v151, vcc, 0, v159, vcc
	v_add_co_u32_e32 v154, vcc, s7, v158
	global_load_dwordx4 v[146:149], v[146:147], off offset:256
	s_nop 0
	v_addc_co_u32_e32 v155, vcc, 0, v159, vcc
	v_add_co_u32_e32 v158, vcc, s8, v158
	global_load_dwordx4 v[150:153], v[150:151], off offset:256
	s_nop 0
	v_addc_co_u32_e32 v159, vcc, 0, v159, vcc
	v_add_co_u32_e32 v166, vcc, s96, v174
	global_load_dwordx4 v[154:157], v[154:155], off offset:256
	s_nop 0
	v_addc_co_u32_e32 v167, vcc, 0, v175, vcc
	v_add_co_u32_e32 v170, vcc, s97, v174
	global_load_dwordx4 v[162:165], v[158:159], off offset:256
	s_nop 0
	global_load_dwordx4 v[158:161], v[174:175], off offset:256
	v_addc_co_u32_e32 v171, vcc, 0, v175, vcc
	v_add_co_u32_e32 v174, vcc, s4, v174
	global_load_dwordx4 v[166:169], v[166:167], off offset:256
	s_nop 0
	v_addc_co_u32_e32 v175, vcc, 0, v175, vcc
	global_load_dwordx4 v[170:173], v[170:171], off offset:256
	s_waitcnt lgkmcnt(12)
	v_mfma_f32_32x32x16_bf16 v[16:31], v[202:205], v[244:247], v[16:31]
	global_load_dwordx4 v[174:177], v[174:175], off offset:256
	s_waitcnt lgkmcnt(0)
	s_cselect_b32 s29, 0, s29
	s_add_i32 s28, s28, 1
	s_cmp_eq_u32 s28, 16
	s_barrier
	v_mfma_f32_32x32x16_bf16 v[0:15], v[234:237], v[244:247], v[0:15]
	s_cbranch_scc0 .LBB0_975
	s_setprio 0
	v_readlane_b32 s2, v254, 2
	s_add_i32 s25, s25, s2
	s_cmpk_gt_i32 s25, 0x3ff
	s_cselect_b64 s[38:39], -1, 0
	s_cmpk_lt_i32 s25, 0x400
	s_mov_b32 s28, s27
	s_mov_b32 s29, s26
	v_readlane_b32 s3, v254, 3
	s_cbranch_scc0 .LBB0_973
	s_ashr_i32 s3, s25, 31
	s_ashr_i32 s2, s25, 3
	s_lshr_b32 s3, s3, 26
	s_add_i32 s3, s2, s3
	s_andn2_b32 s3, s3, 63
	s_sub_i32 s2, s2, s3
	s_and_b32 s29, s2, 56
	s_and_b32 s28, s25, 7
	s_or_b32 s3, s3, s29
	s_lshr_b32 s29, s2, 3
	s_and_b32 s29, s29, 0x1fffff8
	s_and_b32 s2, s2, 7
	s_or_b32 s3, s3, s28
	s_or_b32 s2, s29, s2
	s_lshl_b32 s29, s3, 8
	s_waitcnt vmcnt(10)
	v_add_u32_e32 v130, s29, v183
	v_ashrrev_i32_e32 v131, 31, v130
	s_lshl_b32 s28, s2, 7
	v_lshlrev_b64 v[130:131], 11, v[130:131]
	v_lshl_add_u64 v[178:179], v[184:185], 0, v[130:131]
	v_add_u32_e32 v130, s28, v183
	v_ashrrev_i32_e32 v131, 31, v130
	v_lshlrev_b64 v[130:131], 11, v[130:131]
	v_lshl_add_u64 v[180:181], v[186:187], 0, v[130:131]
	v_add_co_u32_e32 v130, vcc, s96, v178
	s_nop 1
	v_addc_co_u32_e32 v131, vcc, 0, v179, vcc
	s_waitcnt vmcnt(9)
	v_add_co_u32_e32 v134, vcc, s97, v178
	s_nop 1
	v_addc_co_u32_e32 v135, vcc, 0, v179, vcc
	s_waitcnt vmcnt(8)
	v_add_co_u32_e32 v138, vcc, s4, v178
	global_load_dwordx4 v[130:133], v[130:131], off
	s_nop 0
	global_load_dwordx4 v[134:137], v[134:135], off
	v_addc_co_u32_e32 v139, vcc, 0, v179, vcc
	v_add_co_u32_e32 v142, vcc, s5, v178
	s_nop 1
	v_addc_co_u32_e32 v143, vcc, 0, v179, vcc
	global_load_dwordx4 v[138:141], v[138:139], off
	s_nop 0
	global_load_dwordx4 v[146:149], v[142:143], off
	v_add_co_u32_e32 v142, vcc, 0x50000, v178
	s_nop 1
	v_addc_co_u32_e32 v143, vcc, 0, v179, vcc
	v_add_co_u32_e32 v144, vcc, 0x60000, v178
	s_nop 1
	v_addc_co_u32_e32 v145, vcc, 0, v179, vcc
	s_waitcnt vmcnt(8)
	v_add_co_u32_e32 v162, vcc, 0x70000, v178
	global_load_dwordx4 v[150:153], v[142:143], off
	global_load_dwordx4 v[154:157], v[144:145], off
	v_addc_co_u32_e32 v163, vcc, 0, v179, vcc
	s_waitcnt vmcnt(8)
	v_add_co_u32_e32 v166, vcc, 0x10000, v180
	global_load_dwordx4 v[142:145], v[178:179], off
	global_load_dwordx4 v[158:161], v[180:181], off
	v_addc_co_u32_e32 v167, vcc, 0, v181, vcc
	s_waitcnt vmcnt(9)
	v_add_co_u32_e32 v170, vcc, 0x20000, v180
	global_load_dwordx4 v[162:165], v[162:163], off
	s_nop 0
	global_load_dwordx4 v[166:169], v[166:167], off
	v_addc_co_u32_e32 v171, vcc, 0, v181, vcc
	s_waitcnt vmcnt(10)
	v_add_co_u32_e32 v174, vcc, 0x30000, v180
	s_nop 1
	v_addc_co_u32_e32 v175, vcc, 0, v181, vcc
	global_load_dwordx4 v[170:173], v[170:171], off
	s_nop 0
	global_load_dwordx4 v[174:177], v[174:175], off
	s_branch .LBB0_973

.LBB0_1090:
	s_mul_i32 s2, s27, 0x6000
	v_or_b32_e32 v216, s2, v195
	v_add_u32_e32 v217, s2, v194
	v_add_u32_e32 v200, v216, v197
	v_add_u32_e32 v234, v217, v197
	ds_read_b128 v[190:193], v200 offset:16384
	ds_read_b128 v[200:203], v200 offset:18432
	ds_read_b128 v[204:207], v234
	ds_read_b128 v[208:211], v234 offset:2048
	ds_read_b128 v[212:215], v234 offset:4096
	ds_read_b128 v[234:237], v234 offset:6144
	s_add_i32 s2, s27, 1
	s_waitcnt lgkmcnt(3)
	v_mfma_f32_32x32x16_bf16 v[96:111], v[190:193], v[204:207], v[96:111]
	v_add_u32_e32 v216, v216, v198
	v_mfma_f32_32x32x16_bf16 v[112:127], v[200:203], v[204:207], v[112:127]
	ds_read_b128 v[204:207], v216 offset:16384
	ds_read_b128 v[240:243], v216 offset:18432
	s_waitcnt lgkmcnt(4)
	v_mfma_f32_32x32x16_bf16 v[64:79], v[190:193], v[208:211], v[64:79]
	v_add_u32_e32 v216, v217, v198
	v_mfma_f32_32x32x16_bf16 v[80:95], v[200:203], v[208:211], v[80:95]
	ds_read_b128 v[208:211], v216
	ds_read_b128 v[244:247], v216 offset:2048
	s_waitcnt lgkmcnt(5)
	v_mfma_f32_32x32x16_bf16 v[32:47], v[190:193], v[212:215], v[32:47]
	v_mfma_f32_32x32x16_bf16 v[48:63], v[200:203], v[212:215], v[48:63]
	ds_read_b128 v[212:215], v216 offset:4096
	ds_read_b128 v[248:251], v216 offset:6144
	s_waitcnt lgkmcnt(6)
	v_mfma_f32_32x32x16_bf16 v[0:15], v[190:193], v[234:237], v[0:15]
	v_mfma_f32_32x32x16_bf16 v[16:31], v[200:203], v[234:237], v[16:31]
	s_waitcnt lgkmcnt(3)
	v_mfma_f32_32x32x16_bf16 v[96:111], v[204:207], v[208:211], v[96:111]
	v_mfma_f32_32x32x16_bf16 v[112:127], v[240:243], v[208:211], v[112:127]
	s_waitcnt lgkmcnt(2)
	v_mfma_f32_32x32x16_bf16 v[64:79], v[204:207], v[244:247], v[64:79]
	v_mfma_f32_32x32x16_bf16 v[80:95], v[240:243], v[244:247], v[80:95]
	s_waitcnt lgkmcnt(1)
	v_mfma_f32_32x32x16_bf16 v[32:47], v[204:207], v[212:215], v[32:47]
	v_mfma_f32_32x32x16_bf16 v[48:63], v[240:243], v[212:215], v[48:63]
	s_cmp_lt_i32 s27, 2
	s_cselect_b32 s2, s2, 0
	s_add_i32 s27, s2, 1
	s_add_i32 s3, s2, -2
	s_cmp_gt_i32 s2, 0
	s_cselect_b32 s37, -1, 2
	s_min_u32 s38, s26, 13
	s_add_i32 s37, s37, s2
	s_lshl_b32 s84, s38, 7
	s_cmp_gt_i32 s2, 1
	s_mul_i32 s36, s2, 0x6000
	s_cselect_b32 s2, s3, s27
	v_mov_b32_e32 v190, s2
	v_mov_b32_e32 v191, s37
	v_cndmask_b32_e64 v190, v190, v191, s[42:43]
	v_mad_u64_u32 v[216:217], s[2:3], v190, s9, v[182:183]
	v_or_b32_e32 v217, s36, v195
	v_add_u32_e32 v244, s36, v194
	s_waitcnt lgkmcnt(0)
	v_mfma_f32_32x32x16_bf16 v[0:15], v[204:207], v[248:251], v[0:15]
	v_add_u32_e32 v200, v217, v197
	v_add_u32_e32 v234, v244, v197
	ds_read_b128 v[190:193], v200 offset:16384
	ds_read_b128 v[200:203], v200 offset:18432
	ds_read_b128 v[204:207], v234
	ds_read_b128 v[208:211], v234 offset:2048
	ds_read_b128 v[212:215], v234 offset:4096
	ds_read_b128 v[234:237], v234 offset:6144
	s_barrier
	v_mfma_f32_32x32x16_bf16 v[16:31], v[240:243], v[248:251], v[16:31]
	s_waitcnt lgkmcnt(3)
	v_mfma_f32_32x32x16_bf16 v[96:111], v[190:193], v[204:207], v[96:111]
	v_add_u32_e32 v217, v217, v198
	v_mfma_f32_32x32x16_bf16 v[112:127], v[200:203], v[204:207], v[112:127]
	ds_read_b128 v[204:207], v217 offset:16384
	ds_read_b128 v[240:243], v217 offset:18432
	s_waitcnt lgkmcnt(4)
	v_mfma_f32_32x32x16_bf16 v[64:79], v[190:193], v[208:211], v[64:79]
	v_add_u32_e32 v217, v244, v198
	v_mfma_f32_32x32x16_bf16 v[80:95], v[200:203], v[208:211], v[80:95]
	ds_read_b128 v[208:211], v217
	ds_read_b128 v[244:247], v217 offset:2048
	s_waitcnt lgkmcnt(5)
	v_mfma_f32_32x32x16_bf16 v[32:47], v[190:193], v[212:215], v[32:47]
	v_mfma_f32_32x32x16_bf16 v[48:63], v[200:203], v[212:215], v[48:63]
	ds_read_b128 v[212:215], v217 offset:4096
	ds_read_b128 v[248:251], v217 offset:6144
	s_waitcnt lgkmcnt(6)
	v_mfma_f32_32x32x16_bf16 v[0:15], v[190:193], v[234:237], v[0:15]
	s_waitcnt vmcnt(11)
	ds_write_b128 v216, v[142:145]
	s_waitcnt vmcnt(10)
	ds_write_b128 v216, v[130:133] offset:2048
	s_waitcnt vmcnt(9)
	ds_write_b128 v216, v[134:137] offset:4096
	v_mfma_f32_32x32x16_bf16 v[16:31], v[200:203], v[234:237], v[16:31]
	s_waitcnt lgkmcnt(6)
	v_mfma_f32_32x32x16_bf16 v[96:111], v[204:207], v[208:211], v[96:111]
	s_waitcnt vmcnt(8)
	ds_write_b128 v216, v[138:141] offset:6144
	s_waitcnt vmcnt(7)
	ds_write_b128 v216, v[146:149] offset:8192
	s_waitcnt vmcnt(6)
	ds_write_b128 v216, v[150:153] offset:10240
	v_mfma_f32_32x32x16_bf16 v[112:127], v[240:243], v[208:211], v[112:127]
	s_waitcnt lgkmcnt(8)
	v_mfma_f32_32x32x16_bf16 v[64:79], v[204:207], v[244:247], v[64:79]
	s_waitcnt vmcnt(5)
	ds_write_b128 v216, v[154:157] offset:12288
	s_waitcnt vmcnt(4)
	ds_write_b128 v216, v[162:165] offset:14336
	s_waitcnt vmcnt(3)
	ds_write_b128 v216, v[158:161] offset:16384
	v_mfma_f32_32x32x16_bf16 v[80:95], v[240:243], v[244:247], v[80:95]
	s_waitcnt lgkmcnt(10)
	v_mfma_f32_32x32x16_bf16 v[32:47], v[204:207], v[212:215], v[32:47]
	s_waitcnt vmcnt(2)
	ds_write_b128 v216, v[166:169] offset:18432
	s_waitcnt vmcnt(1)
	ds_write_b128 v216, v[170:173] offset:20480
	s_waitcnt vmcnt(0)
	ds_write_b128 v216, v[174:177] offset:22528
	v_mfma_f32_32x32x16_bf16 v[48:63], v[240:243], v[212:215], v[48:63]
	v_lshl_add_u64 v[158:159], v[178:179], 0, s[84:85]
	v_add_co_u32_e32 v130, vcc, s96, v158
	global_load_dwordx4 v[142:145], v[158:159], off offset:256
	s_nop 0
	v_addc_co_u32_e32 v131, vcc, 0, v159, vcc
	v_add_co_u32_e32 v134, vcc, s97, v158
	v_lshl_add_u64 v[174:175], v[180:181], 0, s[84:85]
	s_nop 0
	v_addc_co_u32_e32 v135, vcc, 0, v159, vcc
	v_add_co_u32_e32 v138, vcc, s4, v158
	global_load_dwordx4 v[130:133], v[130:131], off offset:256
	s_nop 0
	v_addc_co_u32_e32 v139, vcc, 0, v159, vcc
	v_add_co_u32_e32 v146, vcc, s5, v158
	global_load_dwordx4 v[134:137], v[134:135], off offset:256
	s_nop 0
	v_addc_co_u32_e32 v147, vcc, 0, v159, vcc
	v_add_co_u32_e32 v150, vcc, s6, v158
	global_load_dwordx4 v[138:141], v[138:139], off offset:256
	s_nop 0
	v_addc_co_u32_e32 v151, vcc, 0, v159, vcc
	v_add_co_u32_e32 v154, vcc, s7, v158
	global_load_dwordx4 v[146:149], v[146:147], off offset:256
	s_nop 0
	v_addc_co_u32_e32 v155, vcc, 0, v159, vcc
	v_add_co_u32_e32 v158, vcc, s8, v158
	global_load_dwordx4 v[150:153], v[150:151], off offset:256
	s_nop 0
	v_addc_co_u32_e32 v159, vcc, 0, v159, vcc
	v_add_co_u32_e32 v166, vcc, s96, v174
	global_load_dwordx4 v[154:157], v[154:155], off offset:256
	s_nop 0
	v_addc_co_u32_e32 v167, vcc, 0, v175, vcc
	v_add_co_u32_e32 v170, vcc, s97, v174
	global_load_dwordx4 v[162:165], v[158:159], off offset:256
	s_nop 0
	global_load_dwordx4 v[158:161], v[174:175], off offset:256
	v_addc_co_u32_e32 v171, vcc, 0, v175, vcc
	v_add_co_u32_e32 v174, vcc, s4, v174
	global_load_dwordx4 v[166:169], v[166:167], off offset:256
	s_nop 0
	v_addc_co_u32_e32 v175, vcc, 0, v175, vcc
	global_load_dwordx4 v[170:173], v[170:171], off offset:256
	s_waitcnt lgkmcnt(12)
	v_mfma_f32_32x32x16_bf16 v[0:15], v[204:207], v[248:251], v[0:15]
	global_load_dwordx4 v[174:177], v[174:175], off offset:256
	s_waitcnt lgkmcnt(0)
	s_cselect_b32 s27, 0, s27
	s_add_i32 s26, s26, 1
	s_cmp_eq_u32 s26, 16
	s_barrier
	v_mfma_f32_32x32x16_bf16 v[16:31], v[240:243], v[248:251], v[16:31]
	s_cbranch_scc0 .LBB0_1090
	s_setprio 0
	v_readlane_b32 s2, v254, 2
	s_add_i32 s25, s25, s2
	s_cmpk_gt_i32 s25, 0x15ff
	s_cselect_b64 s[36:37], -1, 0
	s_cmpk_lt_i32 s25, 0x1600
	s_mov_b32 s26, s29
	s_mov_b32 s27, s28
	v_readlane_b32 s3, v254, 3
	s_cbranch_scc0 .LBB0_1088
	s_ashr_i32 s2, s25, 3
	s_mul_hi_i32 s3, s2, 0x2e8ba2e9
	s_lshr_b32 s27, s3, 31
	s_ashr_i32 s3, s3, 6
	s_add_i32 s27, s3, s27
	s_mul_i32 s3, s27, 0x160
	s_sub_i32 s2, s2, s3
	s_ashr_i32 s3, s2, 6
	s_lshl_b32 s38, s3, 3
	s_and_b32 s26, s25, 7
	s_sub_i32 s39, 44, s38
	s_cmp_gt_i32 s3, 4
	s_cselect_b32 s39, s39, 8
	s_waitcnt vmcnt(10)
	v_cvt_f32_ubyte0_e32 v130, s39
	v_rcp_iflag_f32_e32 v131, v130
	s_and_b32 s40, s2, 63
	v_cvt_f32_ubyte0_e32 v132, s40
	v_mul_f32_e32 v131, v132, v131
	v_trunc_f32_e32 v131, v131
	v_cvt_u32_f32_e32 v133, v131
	v_fma_f32 v131, -v131, v130, v132
	v_cmp_ge_f32_e64 s[2:3], |v131|, v130
	s_cmp_lg_u64 s[2:3], 0
	v_readfirstlane_b32 s41, v133
	s_addc_u32 s2, s41, 0
	s_and_b32 s3, s2, 0xff
	s_mul_i32 s2, s2, s39
	s_sub_i32 s2, s40, s2
	s_and_b32 s2, s2, 0xff
	s_add_i32 s38, s38, s2
	s_lshl_b32 s2, s27, 6
	s_lshl_b32 s3, s3, 3
	s_add_i32 s3, s3, s2
	s_or_b32 s2, s3, s26
	s_lshl_b32 s27, s2, 8
	v_add_u32_e32 v130, s27, v183
	v_ashrrev_i32_e32 v131, 31, v130
	s_lshl_b32 s26, s38, 7
	v_lshlrev_b64 v[130:131], 11, v[130:131]
	v_lshl_add_u64 v[178:179], v[184:185], 0, v[130:131]
	v_add_u32_e32 v130, s26, v183
	v_ashrrev_i32_e32 v131, 31, v130
	v_lshlrev_b64 v[130:131], 11, v[130:131]
	v_lshl_add_u64 v[180:181], v[186:187], 0, v[130:131]
	v_add_co_u32_e32 v130, vcc, s96, v178
	s_nop 1
	v_addc_co_u32_e32 v131, vcc, 0, v179, vcc
	s_waitcnt vmcnt(9)
	v_add_co_u32_e32 v134, vcc, s97, v178
	s_nop 1
	v_addc_co_u32_e32 v135, vcc, 0, v179, vcc
	s_waitcnt vmcnt(8)
	v_add_co_u32_e32 v138, vcc, s4, v178
	global_load_dwordx4 v[130:133], v[130:131], off
	s_nop 0
	global_load_dwordx4 v[134:137], v[134:135], off
	v_addc_co_u32_e32 v139, vcc, 0, v179, vcc
	v_add_co_u32_e32 v142, vcc, s5, v178
	s_nop 1
	v_addc_co_u32_e32 v143, vcc, 0, v179, vcc
	global_load_dwordx4 v[138:141], v[138:139], off
	s_nop 0
	global_load_dwordx4 v[146:149], v[142:143], off
	v_add_co_u32_e32 v142, vcc, 0x50000, v178
	s_nop 1
	v_addc_co_u32_e32 v143, vcc, 0, v179, vcc
	v_add_co_u32_e32 v144, vcc, 0x60000, v178
	s_nop 1
	v_addc_co_u32_e32 v145, vcc, 0, v179, vcc
	s_waitcnt vmcnt(8)
	v_add_co_u32_e32 v162, vcc, 0x70000, v178
	global_load_dwordx4 v[150:153], v[142:143], off
	global_load_dwordx4 v[154:157], v[144:145], off
	v_addc_co_u32_e32 v163, vcc, 0, v179, vcc
	s_waitcnt vmcnt(8)
	v_add_co_u32_e32 v166, vcc, 0x10000, v180
	global_load_dwordx4 v[142:145], v[178:179], off
	global_load_dwordx4 v[158:161], v[180:181], off
	v_addc_co_u32_e32 v167, vcc, 0, v181, vcc
	s_waitcnt vmcnt(9)
	v_add_co_u32_e32 v170, vcc, 0x20000, v180
	global_load_dwordx4 v[162:165], v[162:163], off
	s_nop 0
	global_load_dwordx4 v[166:169], v[166:167], off
	v_addc_co_u32_e32 v171, vcc, 0, v181, vcc
	s_waitcnt vmcnt(10)
	v_add_co_u32_e32 v174, vcc, 0x30000, v180
	s_nop 1
	v_addc_co_u32_e32 v175, vcc, 0, v181, vcc
	global_load_dwordx4 v[170:173], v[170:171], off
	s_nop 0
	global_load_dwordx4 v[174:177], v[174:175], off
	s_branch .LBB0_1088

.LBB0_1150:
	s_mul_i32 s2, s29, 0x6000
	v_or_b32_e32 v234, s2, v193
	v_add_u32_e32 v240, s2, v192
	v_add_u32_e32 v198, v234, v194
	v_add_u32_e32 v214, v240, v194
	ds_read_b128 v[188:191], v198 offset:16384
	ds_read_b128 v[198:201], v198 offset:18432
	ds_read_b128 v[202:205], v214
	ds_read_b128 v[206:209], v214 offset:2048
	ds_read_b128 v[210:213], v214 offset:4096
	ds_read_b128 v[214:217], v214 offset:6144
	s_add_i32 s2, s29, 1
	s_waitcnt lgkmcnt(3)
	v_mfma_f32_32x32x16_bf16 v[112:127], v[188:191], v[202:205], v[112:127]
	v_add_u32_e32 v234, v234, v195
	v_mfma_f32_32x32x16_bf16 v[96:111], v[198:201], v[202:205], v[96:111]
	ds_read_b128 v[202:205], v234 offset:16384
	ds_read_b128 v[234:237], v234 offset:18432
	s_waitcnt lgkmcnt(4)
	v_mfma_f32_32x32x16_bf16 v[80:95], v[188:191], v[206:209], v[80:95]
	v_add_u32_e32 v244, v240, v195
	v_mfma_f32_32x32x16_bf16 v[64:79], v[198:201], v[206:209], v[64:79]
	ds_read_b128 v[206:209], v244
	ds_read_b128 v[240:243], v244 offset:2048
	s_waitcnt lgkmcnt(5)
	v_mfma_f32_32x32x16_bf16 v[48:63], v[188:191], v[210:213], v[48:63]
	v_mfma_f32_32x32x16_bf16 v[32:47], v[198:201], v[210:213], v[32:47]
	ds_read_b128 v[210:213], v244 offset:4096
	ds_read_b128 v[244:247], v244 offset:6144
	s_waitcnt lgkmcnt(6)
	v_mfma_f32_32x32x16_bf16 v[16:31], v[188:191], v[214:217], v[16:31]
	v_mfma_f32_32x32x16_bf16 v[0:15], v[198:201], v[214:217], v[0:15]
	s_waitcnt lgkmcnt(3)
	v_mfma_f32_32x32x16_bf16 v[112:127], v[202:205], v[206:209], v[112:127]
	v_mfma_f32_32x32x16_bf16 v[96:111], v[234:237], v[206:209], v[96:111]
	s_waitcnt lgkmcnt(2)
	v_mfma_f32_32x32x16_bf16 v[80:95], v[202:205], v[240:243], v[80:95]
	v_mfma_f32_32x32x16_bf16 v[64:79], v[234:237], v[240:243], v[64:79]
	s_waitcnt lgkmcnt(1)
	v_mfma_f32_32x32x16_bf16 v[48:63], v[202:205], v[210:213], v[48:63]
	v_mfma_f32_32x32x16_bf16 v[32:47], v[234:237], v[210:213], v[32:47]
	s_cmp_lt_i32 s29, 2
	s_cselect_b32 s2, s2, 0
	s_add_i32 s29, s2, 1
	s_add_i32 s3, s2, -2
	s_cmp_gt_i32 s2, 0
	s_cselect_b32 s37, -1, 2
	s_min_u32 s38, s28, 41
	s_add_i32 s37, s37, s2
	s_lshl_b32 s84, s38, 7
	s_cmp_gt_i32 s2, 1
	s_mul_i32 s36, s2, 0x6000
	s_cselect_b32 s2, s3, s29
	s_waitcnt lgkmcnt(0)
	v_mfma_f32_32x32x16_bf16 v[0:15], v[234:237], v[244:247], v[0:15]
	v_mov_b32_e32 v188, s2
	v_mov_b32_e32 v189, s37
	v_or_b32_e32 v234, s36, v193
	v_add_u32_e32 v240, s36, v192
	v_cndmask_b32_e64 v188, v188, v189, s[42:43]
	v_add_u32_e32 v198, v234, v194
	v_add_u32_e32 v214, v240, v194
	v_mfma_f32_32x32x16_bf16 v[16:31], v[202:205], v[244:247], v[16:31]
	v_mad_u64_u32 v[248:249], s[2:3], v188, s9, v[182:183]
	ds_read_b128 v[188:191], v198 offset:16384
	ds_read_b128 v[198:201], v198 offset:18432
	ds_read_b128 v[202:205], v214
	ds_read_b128 v[206:209], v214 offset:2048
	ds_read_b128 v[210:213], v214 offset:4096
	ds_read_b128 v[214:217], v214 offset:6144
	s_barrier
	s_waitcnt lgkmcnt(3)
	v_mfma_f32_32x32x16_bf16 v[112:127], v[188:191], v[202:205], v[112:127]
	v_add_u32_e32 v234, v234, v195
	v_mfma_f32_32x32x16_bf16 v[96:111], v[198:201], v[202:205], v[96:111]
	ds_read_b128 v[202:205], v234 offset:16384
	ds_read_b128 v[234:237], v234 offset:18432
	s_waitcnt lgkmcnt(4)
	v_mfma_f32_32x32x16_bf16 v[80:95], v[188:191], v[206:209], v[80:95]
	v_add_u32_e32 v244, v240, v195
	v_mfma_f32_32x32x16_bf16 v[64:79], v[198:201], v[206:209], v[64:79]
	ds_read_b128 v[206:209], v244
	ds_read_b128 v[240:243], v244 offset:2048
	s_waitcnt lgkmcnt(5)
	v_mfma_f32_32x32x16_bf16 v[48:63], v[188:191], v[210:213], v[48:63]
	v_mfma_f32_32x32x16_bf16 v[32:47], v[198:201], v[210:213], v[32:47]
	ds_read_b128 v[210:213], v244 offset:4096
	ds_read_b128 v[244:247], v244 offset:6144
	s_waitcnt lgkmcnt(6)
	v_mfma_f32_32x32x16_bf16 v[16:31], v[188:191], v[214:217], v[16:31]
	s_waitcnt vmcnt(11)
	ds_write_b128 v248, v[142:145]
	s_waitcnt vmcnt(10)
	ds_write_b128 v248, v[130:133] offset:2048
	s_waitcnt vmcnt(9)
	ds_write_b128 v248, v[134:137] offset:4096
	v_mfma_f32_32x32x16_bf16 v[0:15], v[198:201], v[214:217], v[0:15]
	s_waitcnt lgkmcnt(6)
	v_mfma_f32_32x32x16_bf16 v[112:127], v[202:205], v[206:209], v[112:127]
	s_waitcnt vmcnt(8)
	ds_write_b128 v248, v[138:141] offset:6144
	s_waitcnt vmcnt(7)
	ds_write_b128 v248, v[146:149] offset:8192
	s_waitcnt vmcnt(6)
	ds_write_b128 v248, v[150:153] offset:10240
	v_mfma_f32_32x32x16_bf16 v[96:111], v[234:237], v[206:209], v[96:111]
	s_waitcnt lgkmcnt(8)
	v_mfma_f32_32x32x16_bf16 v[80:95], v[202:205], v[240:243], v[80:95]
	s_waitcnt vmcnt(5)
	ds_write_b128 v248, v[154:157] offset:12288
	s_waitcnt vmcnt(4)
	ds_write_b128 v248, v[162:165] offset:14336
	s_waitcnt vmcnt(3)
	ds_write_b128 v248, v[158:161] offset:16384
	v_mfma_f32_32x32x16_bf16 v[64:79], v[234:237], v[240:243], v[64:79]
	s_waitcnt lgkmcnt(10)
	v_mfma_f32_32x32x16_bf16 v[48:63], v[202:205], v[210:213], v[48:63]
	s_waitcnt vmcnt(2)
	ds_write_b128 v248, v[166:169] offset:18432
	s_waitcnt vmcnt(1)
	ds_write_b128 v248, v[170:173] offset:20480
	s_waitcnt vmcnt(0)
	ds_write_b128 v248, v[174:177] offset:22528
	v_mfma_f32_32x32x16_bf16 v[32:47], v[234:237], v[210:213], v[32:47]
	v_lshl_add_u64 v[158:159], v[178:179], 0, s[84:85]
	v_add_co_u32_e32 v130, vcc, s18, v158
	global_load_dwordx4 v[142:145], v[158:159], off offset:256
	s_nop 0
	v_addc_co_u32_e32 v131, vcc, 0, v159, vcc
	v_add_co_u32_e32 v134, vcc, s19, v158
	v_lshl_add_u64 v[174:175], v[180:181], 0, s[84:85]
	s_nop 0
	v_addc_co_u32_e32 v135, vcc, 0, v159, vcc
	v_add_co_u32_e32 v138, vcc, s20, v158
	global_load_dwordx4 v[130:133], v[130:131], off offset:256
	s_nop 0
	v_addc_co_u32_e32 v139, vcc, 0, v159, vcc
	v_add_co_u32_e32 v146, vcc, s21, v158
	global_load_dwordx4 v[134:137], v[134:135], off offset:256
	s_nop 0
	v_addc_co_u32_e32 v147, vcc, 0, v159, vcc
	v_add_co_u32_e32 v150, vcc, s22, v158
	global_load_dwordx4 v[138:141], v[138:139], off offset:256
	s_nop 0
	v_addc_co_u32_e32 v151, vcc, 0, v159, vcc
	v_add_co_u32_e32 v154, vcc, s23, v158
	global_load_dwordx4 v[146:149], v[146:147], off offset:256
	s_nop 0
	v_addc_co_u32_e32 v155, vcc, 0, v159, vcc
	v_add_co_u32_e32 v158, vcc, s24, v158
	global_load_dwordx4 v[150:153], v[150:151], off offset:256
	s_nop 0
	v_addc_co_u32_e32 v159, vcc, 0, v159, vcc
	v_add_co_u32_e32 v166, vcc, s18, v174
	global_load_dwordx4 v[154:157], v[154:155], off offset:256
	s_nop 0
	v_addc_co_u32_e32 v167, vcc, 0, v175, vcc
	v_add_co_u32_e32 v170, vcc, s19, v174
	global_load_dwordx4 v[162:165], v[158:159], off offset:256
	s_nop 0
	global_load_dwordx4 v[158:161], v[174:175], off offset:256
	v_addc_co_u32_e32 v171, vcc, 0, v175, vcc
	v_add_co_u32_e32 v174, vcc, s20, v174
	global_load_dwordx4 v[166:169], v[166:167], off offset:256
	s_nop 0
	v_addc_co_u32_e32 v175, vcc, 0, v175, vcc
	global_load_dwordx4 v[170:173], v[170:171], off offset:256
	s_waitcnt lgkmcnt(12)
	v_mfma_f32_32x32x16_bf16 v[16:31], v[202:205], v[244:247], v[16:31]
	global_load_dwordx4 v[174:177], v[174:175], off offset:256
	s_waitcnt lgkmcnt(0)
	s_cselect_b32 s29, 0, s29
	s_add_i32 s28, s28, 1
	s_cmp_eq_u32 s28, 44
	s_barrier
	v_mfma_f32_32x32x16_bf16 v[0:15], v[234:237], v[244:247], v[0:15]
	s_cbranch_scc0 .LBB0_1150
	s_setprio 0
	v_readlane_b32 s2, v254, 2
	s_add_i32 s25, s25, s2
	s_cmpk_gt_i32 s25, 0x3ff
	s_cselect_b64 s[36:37], -1, 0
	s_cmpk_lt_i32 s25, 0x400
	s_mov_b32 s28, s27
	s_mov_b32 s29, s26
	v_readlane_b32 s3, v254, 3
	s_cbranch_scc0 .LBB0_1148
	s_ashr_i32 s3, s25, 31
	s_ashr_i32 s2, s25, 3
	s_lshr_b32 s3, s3, 26
	s_add_i32 s3, s2, s3
	s_andn2_b32 s3, s3, 63
	s_sub_i32 s2, s2, s3
	s_and_b32 s29, s2, 56
	s_and_b32 s28, s25, 7
	s_or_b32 s3, s3, s29
	s_lshr_b32 s29, s2, 3
	s_and_b32 s29, s29, 0x1fffff8
	s_and_b32 s2, s2, 7
	s_or_b32 s3, s3, s28
	s_or_b32 s2, s29, s2
	s_lshl_b32 s29, s3, 8
	s_lshl_b32 s28, s2, 7
	s_waitcnt vmcnt(10)
	v_add_u32_e32 v130, s29, v183
	v_mad_i64_i32 v[178:179], s[2:3], v130, s83, v[184:185]
	v_add_u32_e32 v130, s28, v183
	v_mad_i64_i32 v[180:181], s[2:3], v130, s83, v[186:187]
	v_add_co_u32_e32 v130, vcc, s18, v178
	s_nop 1
	v_addc_co_u32_e32 v131, vcc, 0, v179, vcc
	s_waitcnt vmcnt(9)
	v_add_co_u32_e32 v134, vcc, s19, v178
	s_nop 1
	v_addc_co_u32_e32 v135, vcc, 0, v179, vcc
	s_waitcnt vmcnt(8)
	v_add_co_u32_e32 v138, vcc, s20, v178
	global_load_dwordx4 v[130:133], v[130:131], off
	s_nop 0
	global_load_dwordx4 v[134:137], v[134:135], off
	v_addc_co_u32_e32 v139, vcc, 0, v179, vcc
	v_add_co_u32_e32 v142, vcc, s21, v178
	s_nop 1
	v_addc_co_u32_e32 v143, vcc, 0, v179, vcc
	global_load_dwordx4 v[138:141], v[138:139], off
	s_nop 0
	global_load_dwordx4 v[146:149], v[142:143], off
	v_add_co_u32_e32 v142, vcc, 0xdc000, v178
	s_nop 1
	v_addc_co_u32_e32 v143, vcc, 0, v179, vcc
	v_add_co_u32_e32 v144, vcc, 0x108000, v178
	s_nop 1
	v_addc_co_u32_e32 v145, vcc, 0, v179, vcc
	s_waitcnt vmcnt(8)
	v_add_co_u32_e32 v162, vcc, 0x134000, v178
	global_load_dwordx4 v[150:153], v[142:143], off
	global_load_dwordx4 v[154:157], v[144:145], off
	v_addc_co_u32_e32 v163, vcc, 0, v179, vcc
	s_waitcnt vmcnt(8)
	v_add_co_u32_e32 v166, vcc, 0x2c000, v180
	global_load_dwordx4 v[142:145], v[178:179], off
	global_load_dwordx4 v[158:161], v[180:181], off
	v_addc_co_u32_e32 v167, vcc, 0, v181, vcc
	s_waitcnt vmcnt(9)
	v_add_co_u32_e32 v170, vcc, 0x58000, v180
	global_load_dwordx4 v[162:165], v[162:163], off
	s_nop 0
	global_load_dwordx4 v[166:169], v[166:167], off
	v_addc_co_u32_e32 v171, vcc, 0, v181, vcc
	s_waitcnt vmcnt(10)
	v_add_co_u32_e32 v174, vcc, 0x84000, v180
	s_nop 1
	v_addc_co_u32_e32 v175, vcc, 0, v181, vcc
	global_load_dwordx4 v[170:173], v[170:171], off
	s_nop 0
	global_load_dwordx4 v[174:177], v[174:175], off
	s_branch .LBB0_1148
